# phase1-rstd-3-rows-in-flight
# baseline (speedup 1.0000x reference)
; __device__ void phase1(const Params& p, LAS unsigned char* lds) {
;     ...
;         for (int t = (has_halo ? -15 : 0) + wave; t < 128; t += 8) {
;             const float* xr = p.x + (r0 + t) * D + lane * 4; float ss = 0.f;
; #pragma unroll
;             for (int i = 0; i < 8; ++i) { const f32x4 v = *(const f32x4*)(xr + i * 256); ss += v[0] * v[0] + v[1] * v[1] + v[2] * v[2] + v[3] * v[3]; }
;             ss = wave_sum(ss);
;             if (lane == 0) rs[t + 15] = 1.0f / sqrtf(ss * (1.0f / D) + EPS);
;         }
.LBB0_137:
	s_ashr_i32 s31, s30, 31
	s_lshl_b64 s[34:35], s[30:31], 20
	s_and_b32 s0, s30, 0x7f
	s_cmp_lg_u32 s0, 0
	s_cselect_b64 s[36:37], -1, 0
	s_cmp_eq_u32 s0, 0
	s_cselect_b64 s[38:39], -1, 0
	s_and_b64 s[0:1], s[38:39], exec
	s_cselect_b32 s0, 0, -15
	v_add_u32_e32 v2, s0, v237
	v_ashrrev_i32_e32 v3, 31, v2
	v_lshlrev_b32_e32 v0, 2, v2
	v_lshlrev_b64 v[2:3], 13, v[2:3]
	v_lshl_add_u64 v[2:3], s[34:35], 0, v[2:3]
	v_add3_u32 v0, 0, 60, v0
	s_waitcnt vmcnt(0)
	v_add_u32_e32 v4, s0, v238
	v_lshl_add_u64 v[2:3], v[204:205], 0, v[2:3]
	s_mov_b64 s[40:41], 0
	s_nop 0
	v_readfirstlane_b32 s46, v4
	s_mov_b64 s[0:1], 0x10000
	s_mov_b32 s47, 0xf800000
	s_sub_i32 s46, 0x7f, s46
	s_lshr_b32 s46, s46, 3
.Lrs_loop:
	s_cmp_lt_u32 s46, 3
	s_cbranch_scc1 .Lrs_tail
	v_lshl_add_u64 v[116:117], v[2:3], 0, s[0:1]
	v_lshl_add_u64 v[118:119], v[116:117], 0, s[0:1]
	global_load_dwordx4 v[8:11], v[2:3], off offset:-4096
	global_load_dwordx4 v[12:15], v[2:3], off offset:-3072
	global_load_dwordx4 v[16:19], v[2:3], off offset:-2048
	global_load_dwordx4 v[20:23], v[2:3], off offset:-1024
	global_load_dwordx4 v[24:27], v[2:3], off
	global_load_dwordx4 v[28:31], v[2:3], off offset:1024
	global_load_dwordx4 v[32:35], v[2:3], off offset:2048
	global_load_dwordx4 v[36:39], v[2:3], off offset:3072
	global_load_dwordx4 v[40:43], v[116:117], off offset:-4096
	global_load_dwordx4 v[44:47], v[116:117], off offset:-3072
	global_load_dwordx4 v[48:51], v[116:117], off offset:-2048
	global_load_dwordx4 v[52:55], v[116:117], off offset:-1024
	global_load_dwordx4 v[56:59], v[116:117], off
	global_load_dwordx4 v[60:63], v[116:117], off offset:1024
	global_load_dwordx4 v[64:67], v[116:117], off offset:2048
	global_load_dwordx4 v[68:71], v[116:117], off offset:3072
	global_load_dwordx4 v[72:75], v[118:119], off offset:-4096
	global_load_dwordx4 v[76:79], v[118:119], off offset:-3072
	global_load_dwordx4 v[80:83], v[118:119], off offset:-2048
	global_load_dwordx4 v[84:87], v[118:119], off offset:-1024
	global_load_dwordx4 v[88:91], v[118:119], off
	global_load_dwordx4 v[100:103], v[118:119], off offset:1024
	global_load_dwordx4 v[104:107], v[118:119], off offset:2048
	global_load_dwordx4 v[108:111], v[118:119], off offset:3072
	s_waitcnt vmcnt(16)
	v_mul_f32_e32 v9, v9, v9
	v_mul_f32_e32 v13, v13, v13
	v_mul_f32_e32 v17, v17, v17
	v_mul_f32_e32 v21, v21, v21
	v_mul_f32_e32 v25, v25, v25
	v_mul_f32_e32 v29, v29, v29
	v_mul_f32_e32 v33, v33, v33
	v_mul_f32_e32 v37, v37, v37
	v_fmac_f32_e32 v9, v8, v8
	v_fmac_f32_e32 v13, v12, v12
	v_fmac_f32_e32 v17, v16, v16
	v_fmac_f32_e32 v21, v20, v20
	v_fmac_f32_e32 v25, v24, v24
	v_fmac_f32_e32 v29, v28, v28
	v_fmac_f32_e32 v33, v32, v32
	v_fmac_f32_e32 v37, v36, v36
	v_fmac_f32_e32 v9, v10, v10
	v_fmac_f32_e32 v13, v14, v14
	v_fmac_f32_e32 v17, v18, v18
	v_fmac_f32_e32 v21, v22, v22
	v_fmac_f32_e32 v25, v26, v26
	v_fmac_f32_e32 v29, v30, v30
	v_fmac_f32_e32 v33, v34, v34
	v_fmac_f32_e32 v37, v38, v38
	v_fmac_f32_e32 v9, v11, v11
	v_fmac_f32_e32 v13, v15, v15
	v_fmac_f32_e32 v17, v19, v19
	v_fmac_f32_e32 v21, v23, v23
	v_fmac_f32_e32 v25, v27, v27
	v_fmac_f32_e32 v29, v31, v31
	v_fmac_f32_e32 v33, v35, v35
	v_fmac_f32_e32 v37, v39, v39
	v_add_f32_e32 v5, v9, v13
	v_add_f32_e32 v5, v5, v17
	v_add_f32_e32 v5, v5, v21
	v_add_f32_e32 v5, v5, v25
	v_add_f32_e32 v5, v5, v29
	v_add_f32_e32 v5, v5, v33
	v_add_f32_e32 v5, v5, v37
	s_waitcnt vmcnt(8)
	v_mul_f32_e32 v41, v41, v41
	v_mul_f32_e32 v45, v45, v45
	v_mul_f32_e32 v49, v49, v49
	v_mul_f32_e32 v53, v53, v53
	v_mul_f32_e32 v57, v57, v57
	v_mul_f32_e32 v61, v61, v61
	v_mul_f32_e32 v65, v65, v65
	v_mul_f32_e32 v69, v69, v69
	v_fmac_f32_e32 v41, v40, v40
	v_fmac_f32_e32 v45, v44, v44
	v_fmac_f32_e32 v49, v48, v48
	v_fmac_f32_e32 v53, v52, v52
	v_fmac_f32_e32 v57, v56, v56
	v_fmac_f32_e32 v61, v60, v60
	v_fmac_f32_e32 v65, v64, v64
	v_fmac_f32_e32 v69, v68, v68
	v_fmac_f32_e32 v41, v42, v42
	v_fmac_f32_e32 v45, v46, v46
	v_fmac_f32_e32 v49, v50, v50
	v_fmac_f32_e32 v53, v54, v54
	v_fmac_f32_e32 v57, v58, v58
	v_fmac_f32_e32 v61, v62, v62
	v_fmac_f32_e32 v65, v66, v66
	v_fmac_f32_e32 v69, v70, v70
	v_fmac_f32_e32 v41, v43, v43
	v_fmac_f32_e32 v45, v47, v47
	v_fmac_f32_e32 v49, v51, v51
	v_fmac_f32_e32 v53, v55, v55
	v_fmac_f32_e32 v57, v59, v59
	v_fmac_f32_e32 v61, v63, v63
	v_fmac_f32_e32 v65, v67, v67
	v_fmac_f32_e32 v69, v71, v71
	v_add_f32_e32 v123, v41, v45
	v_add_f32_e32 v123, v123, v49
	v_add_f32_e32 v123, v123, v53
	v_add_f32_e32 v123, v123, v57
	v_add_f32_e32 v123, v123, v61
	v_add_f32_e32 v123, v123, v65
	v_add_f32_e32 v123, v123, v69
	s_waitcnt vmcnt(0)
	v_mul_f32_e32 v73, v73, v73
	v_mul_f32_e32 v77, v77, v77
	v_mul_f32_e32 v81, v81, v81
	v_mul_f32_e32 v85, v85, v85
	v_mul_f32_e32 v89, v89, v89
	v_mul_f32_e32 v101, v101, v101
	v_mul_f32_e32 v105, v105, v105
	v_mul_f32_e32 v109, v109, v109
	v_fmac_f32_e32 v73, v72, v72
	v_fmac_f32_e32 v77, v76, v76
	v_fmac_f32_e32 v81, v80, v80
	v_fmac_f32_e32 v85, v84, v84
	v_fmac_f32_e32 v89, v88, v88
	v_fmac_f32_e32 v101, v100, v100
	v_fmac_f32_e32 v105, v104, v104
	v_fmac_f32_e32 v109, v108, v108
	v_fmac_f32_e32 v73, v74, v74
	v_fmac_f32_e32 v77, v78, v78
	v_fmac_f32_e32 v81, v82, v82
	v_fmac_f32_e32 v85, v86, v86
	v_fmac_f32_e32 v89, v90, v90
	v_fmac_f32_e32 v101, v102, v102
	v_fmac_f32_e32 v105, v106, v106
	v_fmac_f32_e32 v109, v110, v110
	v_fmac_f32_e32 v73, v75, v75
	v_fmac_f32_e32 v77, v79, v79
	v_fmac_f32_e32 v81, v83, v83
	v_fmac_f32_e32 v85, v87, v87
	v_fmac_f32_e32 v89, v91, v91
	v_fmac_f32_e32 v101, v103, v103
	v_fmac_f32_e32 v105, v107, v107
	v_fmac_f32_e32 v109, v111, v111
	v_add_f32_e32 v124, v73, v77
	v_add_f32_e32 v124, v124, v81
	v_add_f32_e32 v124, v124, v85
	v_add_f32_e32 v124, v124, v89
	v_add_f32_e32 v124, v124, v101
	v_add_f32_e32 v124, v124, v105
	v_add_f32_e32 v124, v124, v109
	ds_bpermute_b32 v120, v246, v5
	ds_bpermute_b32 v121, v246, v123
	ds_bpermute_b32 v122, v246, v124
	s_waitcnt lgkmcnt(2)
; __device__ __forceinline__ float wave_sum(float v) {
; #pragma unroll
;     for (int o = 32; o >= 1; o >>= 1) v += __shfl_xor(v, o);
;     return v;
; }
; __device__ void phase1(const Params& p, LAS unsigned char* lds) {
;     ...
;         for (int t = (has_halo ? -15 : 0) + wave; t < 128; t += 8) {
;             const float* xr = p.x + (r0 + t) * D + lane * 4; float ss = 0.f;
; #pragma unroll
;             for (int i = 0; i < 8; ++i) { const f32x4 v = *(const f32x4*)(xr + i * 256); ss += v[0] * v[0] + v[1] * v[1] + v[2] * v[2] + v[3] * v[3]; }
;             ss = wave_sum(ss);
;             if (lane == 0) rs[t + 15] = 1.0f / sqrtf(ss * (1.0f / D) + EPS);
;         }
	v_add_f32_e32 v5, v5, v120
	s_waitcnt lgkmcnt(1)
	v_add_f32_e32 v123, v123, v121
	s_waitcnt lgkmcnt(0)
	v_add_f32_e32 v124, v124, v122
	ds_bpermute_b32 v120, v247, v5
	ds_bpermute_b32 v121, v247, v123
	ds_bpermute_b32 v122, v247, v124
	s_waitcnt lgkmcnt(2)
	v_add_f32_e32 v5, v5, v120
	s_waitcnt lgkmcnt(1)
	v_add_f32_e32 v123, v123, v121
	s_waitcnt lgkmcnt(0)
	v_add_f32_e32 v124, v124, v122
	ds_bpermute_b32 v120, v248, v5
	ds_bpermute_b32 v121, v248, v123
	ds_bpermute_b32 v122, v248, v124
	s_waitcnt lgkmcnt(2)
	v_add_f32_e32 v5, v5, v120
	s_waitcnt lgkmcnt(1)
	v_add_f32_e32 v123, v123, v121
	s_waitcnt lgkmcnt(0)
	v_add_f32_e32 v124, v124, v122
	ds_bpermute_b32 v120, v249, v5
	ds_bpermute_b32 v121, v249, v123
	ds_bpermute_b32 v122, v249, v124
	s_waitcnt lgkmcnt(2)
	v_add_f32_e32 v5, v5, v120
	s_waitcnt lgkmcnt(1)
	v_add_f32_e32 v123, v123, v121
	s_waitcnt lgkmcnt(0)
	v_add_f32_e32 v124, v124, v122
	ds_bpermute_b32 v120, v250, v5
	ds_bpermute_b32 v121, v250, v123
	ds_bpermute_b32 v122, v250, v124
	s_waitcnt lgkmcnt(2)
	v_add_f32_e32 v5, v5, v120
	s_waitcnt lgkmcnt(1)
	v_add_f32_e32 v123, v123, v121
	s_waitcnt lgkmcnt(0)
	v_add_f32_e32 v124, v124, v122
	ds_bpermute_b32 v120, v251, v5
	ds_bpermute_b32 v121, v251, v123
	ds_bpermute_b32 v122, v251, v124
	s_waitcnt lgkmcnt(2)
	v_add_f32_e32 v5, v5, v120
	s_waitcnt lgkmcnt(1)
	v_add_f32_e32 v123, v123, v121
	s_waitcnt lgkmcnt(0)
	v_add_f32_e32 v124, v124, v122
	s_and_saveexec_b64 s[44:45], s[4:5]
	v_fmamk_f32 v5, v5, 0x3a000000, v240
	v_mul_f32_e32 v6, 0x4f800000, v5
	v_cmp_gt_f32_e32 vcc, s47, v5
	s_nop 1
	v_cndmask_b32_e32 v5, v5, v6, vcc
	v_sqrt_f32_e32 v6, v5
	s_nop 0
	v_add_u32_e32 v7, -1, v6
	v_fma_f32 v9, -v7, v6, v5
	v_add_u32_e32 v8, 1, v6
	v_cmp_ge_f32_e64 s[8:9], 0, v9
	s_nop 1
	v_cndmask_b32_e64 v7, v6, v7, s[8:9]
	v_fma_f32 v6, -v8, v6, v5
	v_cmp_lt_f32_e64 s[8:9], 0, v6
	s_nop 1
	v_cndmask_b32_e64 v6, v7, v8, s[8:9]
	v_mul_f32_e32 v7, 0x37800000, v6
	v_cndmask_b32_e32 v6, v6, v7, vcc
	v_cmp_class_f32_e32 vcc, v5, v241
	s_nop 1
	v_cndmask_b32_e32 v5, v6, v5, vcc
	v_div_scale_f32 v6, s[8:9], v5, v5, 1.0
	v_rcp_f32_e32 v7, v6
	s_nop 0
	v_fma_f32 v8, -v6, v7, 1.0
	v_fmac_f32_e32 v7, v8, v7
	v_div_scale_f32 v8, vcc, 1.0, v5, 1.0
	v_mul_f32_e32 v9, v8, v7
	v_fma_f32 v10, -v6, v9, v8
	v_fmac_f32_e32 v9, v10, v7
	v_fma_f32 v6, -v6, v9, v8
	v_div_fmas_f32 v6, v6, v7, v9
	v_div_fixup_f32 v5, v6, v5, 1.0
	ds_write_b32 v0, v5
	v_mov_b32_e32 v5, v123
	v_fmamk_f32 v5, v5, 0x3a000000, v240
	v_mul_f32_e32 v6, 0x4f800000, v5
	v_cmp_gt_f32_e32 vcc, s47, v5
	s_nop 1
	v_cndmask_b32_e32 v5, v5, v6, vcc
	v_sqrt_f32_e32 v6, v5
	s_nop 0
	v_add_u32_e32 v7, -1, v6
	v_fma_f32 v9, -v7, v6, v5
	v_add_u32_e32 v8, 1, v6
	v_cmp_ge_f32_e64 s[8:9], 0, v9
	s_nop 1
	v_cndmask_b32_e64 v7, v6, v7, s[8:9]
	v_fma_f32 v6, -v8, v6, v5
	v_cmp_lt_f32_e64 s[8:9], 0, v6
	s_nop 1
	v_cndmask_b32_e64 v6, v7, v8, s[8:9]
	v_mul_f32_e32 v7, 0x37800000, v6
	v_cndmask_b32_e32 v6, v6, v7, vcc
	v_cmp_class_f32_e32 vcc, v5, v241
	s_nop 1
	v_cndmask_b32_e32 v5, v6, v5, vcc
	v_div_scale_f32 v6, s[8:9], v5, v5, 1.0
	v_rcp_f32_e32 v7, v6
	s_nop 0
	v_fma_f32 v8, -v6, v7, 1.0
	v_fmac_f32_e32 v7, v8, v7
	v_div_scale_f32 v8, vcc, 1.0, v5, 1.0
	v_mul_f32_e32 v9, v8, v7
	v_fma_f32 v10, -v6, v9, v8
	v_fmac_f32_e32 v9, v10, v7
	v_fma_f32 v6, -v6, v9, v8
	v_div_fmas_f32 v6, v6, v7, v9
	v_div_fixup_f32 v5, v6, v5, 1.0
	ds_write_b32 v0, v5 offset:32
	v_mov_b32_e32 v5, v124
	v_fmamk_f32 v5, v5, 0x3a000000, v240
	v_mul_f32_e32 v6, 0x4f800000, v5
	v_cmp_gt_f32_e32 vcc, s47, v5
	s_nop 1
	v_cndmask_b32_e32 v5, v5, v6, vcc
	v_sqrt_f32_e32 v6, v5
	s_nop 0
	v_add_u32_e32 v7, -1, v6
	v_fma_f32 v9, -v7, v6, v5
	v_add_u32_e32 v8, 1, v6
	v_cmp_ge_f32_e64 s[8:9], 0, v9
	s_nop 1
	v_cndmask_b32_e64 v7, v6, v7, s[8:9]
	v_fma_f32 v6, -v8, v6, v5
	v_cmp_lt_f32_e64 s[8:9], 0, v6
	s_nop 1
	v_cndmask_b32_e64 v6, v7, v8, s[8:9]
	v_mul_f32_e32 v7, 0x37800000, v6
	v_cndmask_b32_e32 v6, v6, v7, vcc
	v_cmp_class_f32_e32 vcc, v5, v241
	s_nop 1
	v_cndmask_b32_e32 v5, v6, v5, vcc
	v_div_scale_f32 v6, s[8:9], v5, v5, 1.0
	v_rcp_f32_e32 v7, v6
	s_nop 0
	v_fma_f32 v8, -v6, v7, 1.0
	v_fmac_f32_e32 v7, v8, v7
	v_div_scale_f32 v8, vcc, 1.0, v5, 1.0
	v_mul_f32_e32 v9, v8, v7
	v_fma_f32 v10, -v6, v9, v8
	v_fmac_f32_e32 v9, v10, v7
	v_fma_f32 v6, -v6, v9, v8
	v_div_fmas_f32 v6, v6, v7, v9
	v_div_fixup_f32 v5, v6, v5, 1.0
	ds_write_b32 v0, v5 offset:64
	s_or_b64 exec, exec, s[44:45]
	v_lshl_add_u64 v[2:3], v[118:119], 0, s[0:1]
	v_add_u32_e32 v0, 0x60, v0
	v_add_u32_e32 v4, 24, v4
	s_sub_u32 s46, s46, 3
	s_branch .Lrs_loop
.Lrs_tail:
	s_cmp_eq_u32 s46, 0
	s_cbranch_scc1 .LBB0_141
	s_branch .LBB0_139
